# HGRN chunk-state buffer K0 moved to the idle WS_KK region so step 3 no longer overwrites the pool input; grid barrier after step 2 dropped
# speedup vs baseline: 1.0002x; 1.0002x over previous
; #define LAS __attribute__((address_space(3)))
; __global__ void __launch_bounds__(512) fwd_kernel(Params p) {
;     ...
;     if (threadIdx.x < NSTEPS) {
;         GD g{}; const int fl = build_desc((int)threadIdx.x, p, g);
;         LAS unsigned* t = (LAS unsigned*)(lds + LDS_TAB) + threadIdx.x * TABW;
;         t[0] = (unsigned)fl; put64(t, 2, (unsigned long long)g.A0); put64(t, 4, (unsigned long long)g.B0); t[6] = g.lda; t[7] = g.ldb; t[8] = g.K; t[9] = g.nM; t[10] = g.nN; t[11] = g.nz; t[12] = g.nz2;
;         put64(t, 14, (unsigned long long)g.sA1); put64(t, 16, (unsigned long long)g.sA2); put64(t, 18, (unsigned long long)g.sB1); put64(t, 20, (unsigned long long)g.sB2); t[22] = g.mode; t[23] = g.c0;
;         put64(t, 24, (unsigned long long)g.o0); put64(t, 26, (unsigned long long)g.o1); put64(t, 28, (unsigned long long)g.o2); put64(t, 30, (unsigned long long)g.o3); put64(t, 32, (unsigned long long)g.o4);
;         put64(t, 34, (unsigned long long)g.f0); put64(t, 36, (unsigned long long)g.f1); t[38] = g.ldc; t[39] = g.ro1; t[40] = g.co2; t[41] = __float_as_uint(g.scale); t[42] = g.ro2; put64(t, 44, (unsigned long long)g.f2); t[46] = g.kstA; t[47] = g.kstB; put64(t, 48, (unsigned long long)g.pstA); put64(t, 50, (unsigned long long)g.pstB);
;     }
;     if (threadIdx.x < 4) ((LAS unsigned*)(lds + LDS_BARST))[threadIdx.x] = 0u;
;     __syncthreads();
;     (void)xcd_barrier_post((unsigned*)(p.ws + WS_BAR), (volatile LAS unsigned*)(lds + LDS_BARST));
.LBB0_64:
	s_or_b64 exec, exec, s[0:1]
	v_cmp_gt_u32_e32 vcc, 4, v201
	s_and_saveexec_b64 s[0:1], vcc
	v_lshl_add_u32 v1, v201, 2, 0
	v_add_u32_e32 v1, 0x23000, v1
	v_mov_b32_e32 v2, 0
	ds_write_b32 v1, v2
	v_mov_b32_e32 v2, 0x80
	v_mov_b32_e32 v1, 0x21a5c
	ds_write_b32 v1, v2
	ds_write_b32 v1, v2 offset:512
	v_mov_b32_e32 v2, 0
	v_mov_b32_e32 v1, 0x21200
	ds_write_b32 v1, v2
	s_or_b64 exec, exec, s[0:1]
	s_waitcnt lgkmcnt(0)
	s_barrier
	s_getreg_b32 s4, hwreg(HW_REG_XCC_ID, 0, 4)
	s_mov_b32 s39, 0
	v_cmp_eq_u32_e32 vcc, 0, v201
	s_and_saveexec_b64 s[0:1], vcc
	s_cbranch_execz .LBB0_69
	s_mov_b64 s[2:3], exec
	v_mbcnt_lo_u32_b32 v1, s2, 0
	v_mbcnt_hi_u32_b32 v1, s3, v1
	v_cmp_eq_u32_e32 vcc, 0, v1
	s_and_b64 s[6:7], exec, vcc
	s_mov_b64 exec, s[6:7]
	s_cbranch_execz .LBB0_69
	s_lshl_b32 s4, s4, 8
	s_and_b32 s4, s4, 0xf00
	s_add_u32 s4, s10, s4
	s_addc_u32 s5, s11, 0
	s_bcnt1_i32_b64 s2, s[2:3]
	v_mov_b32_e32 v1, 0x10000
	v_mov_b32_e32 v2, s2
	global_atomic_add v1, v2, s[4:5] offset:1024

; #define LAS __attribute__((address_space(3)))
; #define KIN(i) ((const float*)KPTR(8 * (i)))
; __device__ __forceinline__ bf16_t* kvs_unit(bf16_t* K0, bf16_t* K1, int u) { return (u < 1024 ? K0 : K1) + (size_t)(u & 1023) * 16384; }
; template <int MODE> ...
;     const int lane = tid & 63, w = __builtin_amdgcn_readfirstlane(tid >> 6), fr = lane & 15, fq = lane >> 4;
;     const int k = tid & 127, seg = tid >> 7;
;     LAS bf16_t* QD = (LAS bf16_t*)lds;
;     LAS bf16_t* KD = QD + 64 * 136;
;     LAS float* OUT = (LAS float*)lds;
;     LAS bf16_t* KLT = KD + 64 * 136;
;     LAS bf16_t* VT = KLT + 128 * 72;
;     LAS bf16_t* AM = VT + 128 * 72;
;     LAS bf16_t* ST = AM + 64 * 72;
;     LAS float* SEG = (LAS float*)(ST + 128 * 136) + 128;
;     const int t3 = tid >> 3, sub = tid & 7;
;     const int ti = w >> 1, wh = w & 1;
;     for (int u = blockIdx.x; u < 2048; u += gridDim.x) {
;         const int bh = u >> 6, c = u & 63, b = bh >> 3, h = bh & 7;
;         const int row0 = b * 4096 + c * 64;
;         bf16_t* KVSu = kvs_unit(KVS0, KVS1, u);
;         float lf[16]; unsigned qv[16], vv[16];
;         { const size_t r0_ = (size_t)(row0 + 16 * seg) * 1024 + (size_t)h * 128 + k;
; #pragma unroll
;           for (int j = 0; j < 16; ++j) { const size_t gi = r0_ + (size_t)j * 1024; lf[j] = LOGF[gi]; qv[j] = QF[gi]; vv[j] = VI[gi]; } }
; __global__ void __launch_bounds__(512) fwd_kernel(Params p) {
;     ...
;         case 5: hgrn_pass<1>(lds, (const bf16_t*)(R + R_QF), (const float*)(R + R_LOGF), (const bf16_t*)(ws + WS_KK), (const bf16_t*)(R + R_VI), (const bf16_t*)(R + R_GG), KIN(7), (bf16_t*)(R + R_Y),
;                              (bf16_t*)(R + R_U), (bf16_t*)(ws + WS_XN + 32 * MiB), (float*)(ws + WS_FL), tid); break;
.LBB0_844:
	s_andn2_b64 vcc, exec, s[2:3]
	s_cbranch_vccnz .LBB0_856
	s_cmp_eq_u32 s46, 5
	s_cbranch_scc0 .LBB0_856
	v_readlane_b32 s0, v253, 27
	v_readlane_b32 s1, v253, 28
	s_andn2_b64 vcc, exec, s[0:1]
	v_readfirstlane_b32 s5, v194
	s_cbranch_vccnz .LBB0_856
	s_add_u32 s28, s30, 0x17e00000
	s_addc_u32 s29, s31, 0
	s_add_u32 s42, s30, 0x1de00000
	s_addc_u32 s43, s31, 0
	s_add_u32 s44, s30, 0x19e00000
	s_addc_u32 s45, s31, 0
	v_and_b32_e32 v1, 0x7f, v194
	v_ashrrev_i32_e32 v5, 7, v194
	v_bfe_u32 v4, v194, 4, 2
	v_lshlrev_b32_e32 v7, 3, v194
	v_lshlrev_b32_e32 v8, 4, v194
	s_mov_b32 s59, s46
	s_add_u32 s46, s30, 0x1be00000
	v_and_b32_e32 v2, 0x78, v7
	v_and_b32_e32 v36, 0x70, v8
	v_mul_u32_u24_e32 v8, 0x90, v1
	v_lshlrev_b32_e32 v9, 5, v5
	v_readlane_b32 s15, v254, 5
	v_lshlrev_b32_e32 v11, 4, v4
	s_addc_u32 s47, s31, 0
	v_readlane_b32 s6, v254, 4
	v_add3_u32 v57, 0, v8, v9
	v_lshl_add_u32 v8, v2, 1, s15
	v_add_u32_e32 v15, s15, v11
	s_movk_i32 s15, 0x880
	s_add_u32 s36, s30, 0x25e00000
	s_addc_u32 s37, s31, 0
	s_add_u32 s0, s30, 0x13e00000
	v_lshlrev_b32_e32 v55, 4, v5
	v_lshl_add_u32 v56, v194, 2, s6
	v_lshl_add_u32 v58, v1, 2, s6
	v_cmp_lt_i32_e64 s[6:7], 0, v5
	v_cmp_lt_i32_e64 s[8:9], 1, v5
	v_cmp_lt_i32_e64 s[10:11], 2, v5
	v_mul_lo_u32 v5, v5, s15
	s_addc_u32 s1, s31, 0
	s_ashr_i32 s12, s5, 7
	v_or_b32_e32 v5, v5, v1
	v_and_b32_e32 v3, 15, v194
	s_lshl_b32 s13, s12, 4
	v_lshl_add_u32 v60, v5, 1, 0
	v_add_u32_e32 v5, 0x200, v194
	s_bfe_u32 s5, s5, 0x10006
	v_or_b32_e32 v9, s13, v3
	s_movk_i32 s17, 0x110
	s_movk_i32 s16, 0x90
	v_lshrrev_b32_e32 v5, 4, v5
	v_ashrrev_i32_e32 v37, 3, v194
	v_readlane_b32 s2, v254, 27
	s_lshl_b32 s14, s5, 1
	v_lshl_or_b32 v12, v4, 2, s13
	v_mul_lo_u32 v4, v9, s16
	v_readlane_b32 s22, v254, 6
	s_lshl_b32 s13, s5, 2
	s_movk_i32 s18, 0x210
	v_and_b32_e32 v38, 0xffffff80, v7
	v_mul_lo_u32 v7, v5, s17
	v_add_u32_e32 v5, 0x400, v194
	v_readlane_b32 s3, v254, 28
	v_mul_lo_u32 v10, v9, s17
	v_add_u32_e32 v9, s22, v4
	v_mul_lo_u32 v17, v37, s18
	v_lshlrev_b32_e32 v4, 2, v36
	v_lshrrev_b32_e32 v5, 4, v5
	s_cmp_le_i32 s14, s12
	s_load_dwordx2 s[2:3], s[2:3], 0x38
	v_lshl_add_u32 v16, v3, 2, 0
	v_add3_u32 v59, 0, v17, v4
	v_mul_lo_u32 v17, v5, s17
	v_add_u32_e32 v5, 0x600, v194
	s_cselect_b64 s[48:49], -1, 0
	s_cmp_ge_i32 s14, s12
	v_lshl_or_b32 v14, s5, 6, v3
	v_lshrrev_b32_e32 v5, 4, v5
	v_lshl_or_b32 v19, s5, 5, v3
	s_cselect_b64 s[50:51], -1, 0
	v_lshl_add_u32 v28, s5, 8, v16
	s_or_b32 s5, s13, 1
	v_mul_lo_u32 v18, v5, s17
	v_lshl_or_b32 v5, s5, 4, v3
	v_lshl_add_u32 v30, s5, 6, v16
	s_or_b32 s5, s13, 2
	v_mul_u32_u24_e32 v29, 0x90, v5
	v_lshl_or_b32 v5, s5, 4, v3
	v_or_b32_e32 v25, 16, v19
	v_mul_u32_u24_e32 v31, 0x90, v5
	v_lshl_add_u32 v32, s5, 6, v16
	s_or_b32 s5, s13, 3
	v_mov_b32_e32 v5, v0
	v_lshrrev_b32_e32 v6, 4, v194
	v_mul_lo_u32 v21, v12, s16
	v_lshl_or_b32 v3, s5, 4, v3
	s_waitcnt lgkmcnt(0)
	v_lshl_add_u64 v[46:47], s[2:3], 0, v[4:5]
	v_lshlrev_b32_e32 v5, 1, v25
	v_add_u32_e32 v10, 0, v10
	v_add_u32_e32 v13, 0, v11
	v_add_u32_e32 v40, 0x1000, v38
	v_add_u32_e32 v42, 0x2000, v38
	v_add_u32_e32 v44, 0x3000, v38
	v_mul_lo_u32 v6, v6, s17
	v_mul_u32_u24_e32 v20, 0x110, v19
	v_or_b32_e32 v22, 1, v12
	v_or_b32_e32 v23, 2, v12
	v_or_b32_e32 v24, 3, v12
	v_mul_u32_u24_e32 v26, 0x110, v14
	v_mul_lo_u32 v27, v12, s18
	v_mul_u32_u24_e32 v14, 0x90, v14
	v_mul_u32_u24_e32 v3, 0x90, v3
	v_lshl_add_u32 v16, s5, 6, v16
	v_lshl_add_u32 v4, v19, 1, s22
	v_add3_u32 v61, s22, v21, v5
	s_mov_b32 s60, s33
	v_ashrrev_i32_e32 v39, 31, v38
	v_ashrrev_i32_e32 v41, 31, v40
	v_ashrrev_i32_e32 v43, 31, v42
	v_ashrrev_i32_e32 v45, 31, v44
	v_cmp_gt_i32_e64 s[12:13], v19, v12
	v_cmp_gt_i32_e64 s[14:15], v19, v22
	v_cmp_gt_i32_e64 s[16:17], v19, v23
	v_cmp_gt_i32_e64 s[18:19], v19, v24
	v_cmp_gt_i32_e64 s[20:21], v25, v12
	v_cmp_gt_i32_e64 s[22:23], v25, v22
	v_add_u32_e32 v62, 0x90, v61
	v_cmp_gt_i32_e64 s[24:25], v25, v23
	v_add_u32_e32 v63, 0x120, v61
	v_cmp_gt_i32_e64 s[26:27], v25, v24
	v_add_u32_e32 v64, 0x1b0, v61
	v_lshlrev_b32_e32 v48, 1, v2
	v_add_u32_e32 v65, v8, v6
	v_add_u32_e32 v66, v8, v7
	v_add_u32_e32 v67, v8, v17
	v_add_u32_e32 v68, v8, v18
	v_add_u32_e32 v69, v10, v11
	v_add_u32_e32 v70, v4, v21
	v_add_u32_e32 v71, v15, v26
	v_add_u32_e32 v72, v9, v11
	v_add_u32_e32 v73, v13, v14
	v_add_u32_e32 v74, v28, v27
	v_add_u32_e32 v75, v13, v29
	v_add_u32_e32 v76, v30, v27
	v_add_u32_e32 v77, v13, v31
	v_add_u32_e32 v78, v32, v27
	v_add_u32_e32 v79, v13, v3
	v_add_u32_e32 v80, v16, v27
	v_add_u32_e32 v81, v13, v20
	v_readlane_b32 s5, v253, 4
	v_readlane_b32 s33, v253, 55
	v_readlane_b32 s35, v253, 53
	v_readlane_b32 s52, v253, 51
	s_mov_b32 s53, s58
	s_branch .LBB0_849

; __device__ __forceinline__ bf16_t* kvs_unit(bf16_t* K0, bf16_t* K1, int u) { return (u < 1024 ? K0 : K1) + (size_t)(u & 1023) * 16384; }
; __device__ __forceinline__ void hgrn_scan(bf16_t* KVS0, bf16_t* KVS1, const float* DLG, const int tid) {
;     for (int blk = blockIdx.x; blk < 256; blk += gridDim.x) {
;         const int bh = blk >> 3, e = (blk & 7) * 512 + tid, v = e >> 5, k4 = (e & 31) * 4;
;         f32x4 S = (f32x4){0.f, 0.f, 0.f, 0.f};
;         for (int c0 = 0; c0 < 64; c0 += 8) {
;             u32x2 kvw[8]; f32x4 dl[8];
; #pragma unroll
;             for (int i = 0; i < 8; ++i) { const int u = bh * 64 + c0 + i; kvw[i] = *(const u32x2*)(kvs_unit(KVS0, KVS1, u) + v * 128 + k4); dl[i] = *(const f32x4*)(DLG + (size_t)u * 128 + k4); }
; __global__ void __launch_bounds__(512) fwd_kernel(Params p) {
;     ...
;         case 4: hgrn_scan((bf16_t*)(R + R_U), (bf16_t*)(ws + WS_XN + 32 * MiB), (const float*)(ws + WS_FL), tid); break;
.LBB0_857:
	s_andn2_b64 vcc, exec, s[2:3]
	s_cbranch_vccnz .LBB0_1306
	s_cmp_lt_i32 s46, 3
	s_mov_b64 s[2:3], -1
	s_cbranch_scc1 .LBB0_1294
	s_cmp_gt_i32 s46, 3
	s_cbranch_scc0 .LBB0_866
	v_readlane_b32 s0, v253, 29
	v_readlane_b32 s1, v253, 30
	s_andn2_b64 vcc, exec, s[0:1]
	s_mov_b64 s[12:13], 0x1000
	s_cbranch_vccnz .LBB0_865
	v_lshlrev_b32_e32 v1, 2, v194
	v_and_b32_e32 v2, 0x7c, v1
	v_and_b32_e32 v1, 31, v194
	v_lshlrev_b32_e32 v4, 4, v1
	v_mov_b32_e32 v5, v0
	s_add_u32 s36, s30, 0x25e00000
	s_addc_u32 s37, s31, 0
	s_add_u32 s0, s30, 0x13e00000
	v_lshl_add_u64 v[4:5], s[30:31], 0, v[4:5]
	s_mov_b64 s[2:3], 0x100e00
	s_addc_u32 s1, s31, 0
	v_lshl_add_u64 v[30:31], v[4:5], 0, s[2:3]
	v_lshlrev_b32_e32 v32, 1, v2
	v_readlane_b32 s2, v253, 4
	s_mov_b32 s3, s58

; #define LAS __attribute__((address_space(3)))
; #define KIN(i) ((const float*)KPTR(8 * (i)))
; __device__ __forceinline__ bf16_t* kvs_unit(bf16_t* K0, bf16_t* K1, int u) { return (u < 1024 ? K0 : K1) + (size_t)(u & 1023) * 16384; }
; template <int MODE> ...
;     const int lane = tid & 63, w = __builtin_amdgcn_readfirstlane(tid >> 6), fr = lane & 15, fq = lane >> 4;
;     const int k = tid & 127, seg = tid >> 7;
;     LAS bf16_t* QD = (LAS bf16_t*)lds;
;     LAS bf16_t* KD = QD + 64 * 136;
;     LAS float* OUT = (LAS float*)lds;
;     LAS bf16_t* KLT = KD + 64 * 136;
;     LAS bf16_t* VT = KLT + 128 * 72;
;     LAS bf16_t* AM = VT + 128 * 72;
;     LAS bf16_t* ST = AM + 64 * 72;
;     LAS float* SEG = (LAS float*)(ST + 128 * 136) + 128;
;     const int t3 = tid >> 3, sub = tid & 7;
;     const int ti = w >> 1, wh = w & 1;
; __global__ void __launch_bounds__(512) fwd_kernel(Params p) {
;     ...
;                 __syncthreads();
;                 hgrn_pass<0>(lds, (const bf16_t*)(R + R_QF), (const float*)(R + R_LOGF), (const bf16_t*)(ws + WS_KK), (const bf16_t*)(R + R_VI), (const bf16_t*)(R + R_GG), KIN(7), (bf16_t*)(R + R_Y),
;                              (bf16_t*)(R + R_U), (bf16_t*)(ws + WS_XN + 32 * MiB), (float*)(ws + WS_FL), tid);
.LBB0_1288:
	v_readlane_b32 s0, v253, 27
	v_readlane_b32 s1, v253, 28
	v_readlane_b32 s44, v253, 2
	v_readlane_b32 s42, v254, 21
	s_andn2_b64 vcc, exec, s[0:1]
	v_readfirstlane_b32 s2, v194
	v_readlane_b32 s45, v253, 3
	s_movk_i32 s25, 0x1400
	s_mov_b32 s46, s59
	v_readlane_b32 s43, v254, 22
	s_mov_b32 s33, s60
	s_waitcnt vmcnt(0)
	s_barrier
	s_cbranch_vccnz .LBB0_1293
	s_add_u32 s14, s30, 0x1de00000
	v_and_b32_e32 v1, 0x7f, v194
	s_addc_u32 s15, s31, 0
	v_ashrrev_i32_e32 v3, 7, v194
	v_mul_u32_u24_e32 v2, 0x48, v1
	s_add_u32 s16, s30, 0x19e00000
	v_lshlrev_b32_e32 v2, 1, v2
	v_lshlrev_b32_e32 v6, 5, v3
	s_addc_u32 s17, s31, 0
	v_readlane_b32 s3, v254, 4
	v_add3_u32 v20, 0, v2, v6
	v_lshlrev_b32_e32 v2, 2, v1
	s_add_u32 s36, s30, 0x25e00000
	s_addc_u32 s37, s31, 0
	s_add_u32 s0, s30, 0x13e00000
	v_lshlrev_b32_e32 v18, 4, v3
	v_lshl_add_u32 v19, v194, 2, s3
	v_add_u32_e32 v21, s3, v2
	v_cmp_lt_i32_e64 s[6:7], 0, v3
	v_cmp_lt_i32_e64 s[8:9], 1, v3
	v_cmp_lt_i32_e64 s[10:11], 2, v3
	s_movk_i32 s3, 0x80
	v_mov_b32_e32 v3, v0
	s_addc_u32 s1, s31, 0
	v_cmp_gt_u32_e64 s[12:13], s3, v194
	v_lshl_add_u64 v[2:3], s[30:31], 0, v[2:3]
	s_mov_b64 s[18:19], 0x100000
	s_ashr_i32 s3, s2, 2
	v_lshl_add_u64 v[10:11], v[2:3], 0, s[18:19]
	s_and_b32 s2, s3, -16
	v_bfi_b32 v2, -16, s3, v194
	s_movk_i32 s3, 0x90
	v_and_b32_e32 v5, 15, v194
	v_bfe_u32 v4, v194, 4, 2
	v_mul_lo_u32 v2, v2, s3
	v_add_u32_e32 v3, 0, v2
	v_lshlrev_b32_e32 v6, 4, v4
	v_lshlrev_b32_e32 v2, 7, v5
	v_mul_u32_u24_e32 v5, 0x90, v5
	s_ashr_i32 s3, s2, 31
	v_lshlrev_b32_e32 v4, 2, v4
	v_add3_u32 v22, 0, v6, v5
	v_add_u32_e32 v23, 0xd000, v22
	v_add_u32_e32 v24, v3, v6
	s_lshl_b64 s[18:19], s[2:3], 1
	v_lshlrev_b32_e32 v12, 1, v4
	v_lshlrev_b32_e32 v14, 1, v2
	v_readlane_b32 s5, v253, 4
	v_readlane_b32 s22, v253, 55
	v_readlane_b32 s23, v253, 53
	v_readlane_b32 s24, v253, 51
	s_mov_b32 s20, s58
	s_branch .LBB0_1291
